# v7 + mLSTM output waves: score-product K fragments read ahead (6 deep) and output-gate loads issued before the chunk barrier
# baseline (speedup 1.0000x reference)
; #define GAS __attribute__((address_space(1)))
; #define LAS __attribute__((address_space(3)))
; __device__ __forceinline__ float fexp(float x) { return __builtin_amdgcn_exp2f(x * LOG2E); }
; __device__ __forceinline__ float bflo(unsigned w) { return __uint_as_float(w << 16); }
; __device__ __forceinline__ float bfhi(unsigned w) { return __uint_as_float(w & 0xffff0000u); }
; __device__ __forceinline__ void ml_out_unit(LAS unsigned char* lds, const MixBufs& B, int b, int h, int seg, int tid) {
;     ...
;             __syncthreads();
;             LAS unsigned char* CTc = lds + (cur ? O_CT1 : O_CT0); const LAS float* NVc = (const LAS float*)(lds + (cur ? O_NV1 : O_NV0));
;             const float fct = FC[16 * ti + c];
;             float mx = -INFINITY;
; #pragma unroll
;             for (int s4 = 0; s4 < 4; ++s4) { const f32x4 l4 = *(const LAS f32x4*)(LI + 16 * g + 4 * s4), f4 = *(const LAS f32x4*)(FC + 16 * g + 4 * s4);
; #pragma unroll
;                 for (int e = 0; e < 4; ++e) mx = fmaxf(mx, l4[e] - fabsf(fct - f4[e])); }
;             mx = fmaxf(mx, __shfl_xor(mx, 16)); mx = fmaxf(mx, __shfl_xor(mx, 32));
;             const float gi = fct + m, mt = fmaxf(gi, mx), sc = fexp(gi - mt);
;             bf16x8 qf[4];
; #pragma unroll
;             for (int kk = 0; kk < 4; ++kk) qf[kk] = frag_row(lds + O_Q, GP128, 16 * ti, 32 * kk, lane);
;             float qn = 0.f;
; #pragma unroll
;             for (int kk = 0; kk < 4; ++kk) { const v4u qq = __builtin_bit_cast(v4u, qf[kk]); const f32x4 n0 = *(const LAS f32x4*)(NVc + 32 * kk + 8 * g), n1 = *(const LAS f32x4*)(NVc + 32 * kk + 8 * g + 4);
;                 qn += (bflo(qq.x) * n0[0] + bfhi(qq.x) * n0[1]) + (bflo(qq.y) * n0[2] + bfhi(qq.y) * n0[3]) + (bflo(qq.z) * n1[0] + bfhi(qq.z) * n1[1]) + (bflo(qq.w) * n1[2] + bfhi(qq.w) * n1[3]); }
;             qn += __shfl_xor(qn, 16); qn += __shfl_xor(qn, 32);
;     ...
;             for (int vt = 0; vt < 8; ++vt) opv[vt] = *(const GAS u32x2*)(B.PROJ + trow * NPROJ + PC_OP + h * 128 + 16 * vt + 4 * g);
.LBB0_672:
	v_add_f32_e32 v2, v186, v12
	v_max_f32_e32 v12, v13, v13
	v_max_f32_e32 v198, v2, v12
	v_lshl_add_u64 v[82:83], s[88:89], 0, v[64:65]
	global_load_dwordx2 v[98:99], v[82:83], off offset:-128
	global_load_dwordx2 v[94:95], v[82:83], off offset:-96
	global_load_dwordx2 v[92:93], v[82:83], off offset:-64
	global_load_dwordx2 v[90:91], v[82:83], off offset:-32
	global_load_dwordx2 v[88:89], v[82:83], off
	global_load_dwordx2 v[86:87], v[82:83], off offset:32
	global_load_dwordx2 v[84:85], v[82:83], off offset:64
	global_load_dwordx2 v[82:83], v[82:83], off offset:96
	s_waitcnt lgkmcnt(0)
	s_barrier
	ds_read_b128 v[214:217], v170 offset:17408
	ds_read_b128 v[218:221], v170 offset:17472
	ds_read_b128 v[222:225], v170 offset:17536
	ds_read_b128 v[226:229], v170 offset:17600
	ds_read_b128 v[230:233], v170 offset:21760
	ds_read_b128 v[234:237], v170 offset:21824
	ds_read_b32 v2, v157
	ds_read_b128 v[12:15], v159
	ds_read_b128 v[16:19], v159 offset:16
	ds_read_b128 v[20:23], v159 offset:32
	ds_read_b128 v[24:27], v159 offset:48
	ds_read_b128 v[28:31], v160
	ds_read_b128 v[32:35], v160 offset:16
	ds_read_b128 v[36:39], v160 offset:32
	ds_read_b128 v[40:43], v160 offset:48
	s_mov_b32 s5, 0xff800000
	s_waitcnt lgkmcnt(3)
	v_sub_f32_e32 v28, v2, v28
	v_sub_f32_e64 v12, v12, |v28|
	v_sub_f32_e32 v28, v2, v29
	v_sub_f32_e64 v13, v13, |v28|
	v_max3_f32 v12, v12, s5, v13
	v_sub_f32_e32 v13, v2, v30
	v_sub_f32_e64 v13, v14, |v13|
	v_sub_f32_e32 v14, v2, v31
	v_sub_f32_e64 v14, v15, |v14|
	v_max3_f32 v12, v12, v13, v14
	s_waitcnt lgkmcnt(2)
	v_sub_f32_e32 v13, v2, v32
	v_sub_f32_e32 v14, v2, v33
	v_sub_f32_e64 v13, v16, |v13|
	v_sub_f32_e64 v14, v17, |v14|
	v_max3_f32 v12, v12, v13, v14
	v_sub_f32_e32 v13, v2, v34
	v_sub_f32_e32 v14, v2, v35
	v_sub_f32_e64 v13, v18, |v13|
	v_sub_f32_e64 v14, v19, |v14|
	v_max3_f32 v12, v12, v13, v14
	s_waitcnt lgkmcnt(1)
	v_sub_f32_e32 v13, v2, v36
	v_sub_f32_e32 v14, v2, v37
	v_sub_f32_e64 v13, v20, |v13|
	v_sub_f32_e64 v14, v21, |v14|
	v_max3_f32 v12, v12, v13, v14
	v_sub_f32_e32 v13, v2, v38
	v_sub_f32_e32 v14, v2, v39
	v_sub_f32_e64 v13, v22, |v13|
	v_sub_f32_e64 v14, v23, |v14|
	v_max3_f32 v12, v12, v13, v14
	s_waitcnt lgkmcnt(0)
	v_sub_f32_e32 v13, v2, v40
	v_sub_f32_e32 v14, v2, v41
	v_sub_f32_e64 v13, v24, |v13|
	v_sub_f32_e64 v14, v25, |v14|
	v_max3_f32 v12, v12, v13, v14
	v_sub_f32_e32 v13, v2, v42
	v_sub_f32_e32 v14, v2, v43
	v_sub_f32_e64 v13, v26, |v13|
	v_sub_f32_e64 v14, v27, |v14|
	v_max3_f32 v12, v12, v13, v14
	v_and_b32_e32 v14, 64, v183
	v_xor_b32_e32 v13, 16, v183
	v_add_u32_e32 v14, 64, v14
	v_cmp_lt_i32_e32 vcc, v13, v14
	s_cmp_eq_u32 s7, 0
	s_cselect_b32 s5, 0x22000, s97
	v_cndmask_b32_e32 v13, v183, v13, vcc
	v_lshlrev_b32_e32 v200, 2, v13
	ds_bpermute_b32 v13, v200, v12
	v_add_u32_e32 v47, s5, v163
	s_cselect_b32 s4, 0x11000, s96
	s_waitcnt lgkmcnt(0)
	v_max_f32_e32 v13, v13, v13
	v_max_f32_e32 v12, v12, v13
	v_xor_b32_e32 v13, 32, v183
	v_cmp_lt_i32_e32 vcc, v13, v14
	v_add_f32_e32 v14, v186, v2
	s_nop 0
	v_cndmask_b32_e32 v13, v183, v13, vcc
	v_lshlrev_b32_e32 v199, 2, v13
	ds_bpermute_b32 v13, v199, v12
	s_waitcnt lgkmcnt(0)
	v_max3_f32 v102, v14, v12, v13
	v_sub_f32_e32 v12, v14, v102
	v_mul_f32_e32 v46, 0x3fb8aa3b, v12
	v_add_u32_e32 v12, v161, v158
	ds_read_b128 v[24:27], v12
	ds_read_b128 v[20:23], v12 offset:64
	ds_read_b128 v[16:19], v12 offset:128
	ds_read_b128 v[12:15], v12 offset:192
	ds_read_b128 v[28:31], v47
	ds_read_b128 v[32:35], v47 offset:16
	s_waitcnt lgkmcnt(5)
	v_lshlrev_b32_e32 v40, 16, v24
	v_and_b32_e32 v41, 0xffff0000, v25
	v_and_b32_e32 v36, 0xffff0000, v24
	s_waitcnt lgkmcnt(1)
	v_mov_b32_e32 v38, v29
	v_mov_b32_e32 v29, v31
	v_lshlrev_b32_e32 v37, 16, v25
	v_mov_b32_e32 v39, v30
	v_pk_mul_f32 v[28:29], v[28:29], v[40:41]
	v_and_b32_e32 v41, 0xffff0000, v21
	v_pk_fma_f32 v[44:45], v[38:39], v[36:37], v[28:29]
	ds_read_b128 v[28:31], v47 offset:128
	ds_read_b128 v[36:39], v47 offset:144
	v_lshlrev_b32_e32 v40, 16, v21
	v_and_b32_e32 v51, 0xffff0000, v20
	v_and_b32_e32 v50, 0xffff0000, v22
	s_waitcnt lgkmcnt(1)
	v_mul_f32_e32 v42, v31, v41
	v_pk_fma_f32 v[30:31], v[30:31], v[40:41], v[42:43] op_sel_hi:[1,1,0]
	v_mov_b32_e32 v43, v28
	s_waitcnt lgkmcnt(0)
	v_mov_b32_e32 v28, v37
	v_lshlrev_b32_e32 v41, 16, v20
	v_lshlrev_b32_e32 v40, 16, v22
	v_mov_b32_e32 v42, v36
	v_pk_mul_f32 v[28:29], v[28:29], v[50:51]
	v_and_b32_e32 v49, 0xffff0000, v26
	v_pk_fma_f32 v[28:29], v[42:43], v[40:41], v[28:29]
	v_lshlrev_b32_e32 v48, 16, v26
	v_pk_add_f32 v[30:31], v[28:29], v[30:31] op_sel:[1,0] op_sel_hi:[0,1]
	v_pk_add_f32 v[36:37], v[28:29], v[30:31]
	ds_read_b128 v[28:31], v47 offset:256
	ds_read_b128 v[40:43], v47 offset:272
	v_lshlrev_b32_e32 v37, 16, v17
	v_and_b32_e32 v51, 0xffff0000, v23
	v_lshlrev_b32_e32 v50, 16, v23
	s_waitcnt lgkmcnt(1)
	v_mul_f32_e32 v70, v30, v37
	v_and_b32_e32 v30, 0xffff0000, v17
	v_mul_f32_e32 v71, v31, v30
	v_lshlrev_b32_e32 v30, 16, v18
	v_and_b32_e32 v31, 0xffff0000, v18
	s_waitcnt lgkmcnt(0)
; #define LAS __attribute__((address_space(3)))
; #define MFMA16(a, b, c) __builtin_amdgcn_mfma_f32_16x16x32_bf16((a), (b), (c), 0, 0, 0)
; __device__ __forceinline__ float fexp(float x) { return __builtin_amdgcn_exp2f(x * LOG2E); }
; __device__ __forceinline__ float bflo(unsigned w) { return __uint_as_float(w << 16); }
; __device__ __forceinline__ float bfhi(unsigned w) { return __uint_as_float(w & 0xffff0000u); }
; __device__ __forceinline__ unsigned cvtpk(float lo, float hi) { const f32x2_t v = {lo, hi}; const bf16x2_t b = __builtin_convertvector(v, bf16x2_t); return __builtin_bit_cast(unsigned, b); }
; __device__ __forceinline__ void ml_out_unit(LAS unsigned char* lds, const MixBufs& B, int b, int h, int seg, int tid) {
;     ...
;             for (int kk = 0; kk < 4; ++kk) { const v4u qq = __builtin_bit_cast(v4u, qf[kk]); const f32x4 n0 = *(const LAS f32x4*)(NVc + 32 * kk + 8 * g), n1 = *(const LAS f32x4*)(NVc + 32 * kk + 8 * g + 4);
;                 qn += (bflo(qq.x) * n0[0] + bfhi(qq.x) * n0[1]) + (bflo(qq.y) * n0[2] + bfhi(qq.y) * n0[3]) + (bflo(qq.z) * n1[0] + bfhi(qq.z) * n1[1]) + (bflo(qq.w) * n1[2] + bfhi(qq.w) * n1[3]); }
;             qn += __shfl_xor(qn, 16); qn += __shfl_xor(qn, 32);
;             float dsum = 0.f; bf16x8 pb[2];
; #pragma unroll
;             for (int ks = 0; ks < 2; ++ks) { f32x4 p2[2];
; #pragma unroll
;                 for (int jj = 0; jj < 2; ++jj) { const int sj = 2 * ks + jj;
;                     f32x4 acc = (f32x4){0.f, 0.f, 0.f, 0.f};
; #pragma unroll
;                     for (int kk = 0; kk < 4; ++kk) acc = MFMA16(frag_row(lds + O_K, GP128, 16 * sj, 32 * kk, lane), qf[kk], acc);
;                     const f32x4 li4 = *(const LAS f32x4*)(LI + 16 * sj + 4 * g), fc4 = *(const LAS f32x4*)(FC + 16 * sj + 4 * g);
; #pragma unroll
;                     for (int i = 0; i < 4; ++i) { p2[jj][i] = acc[i] * fexp(li4[i] - fabsf(fct - fc4[i]) - mt); dsum += p2[jj][i]; } }
;                 v4u pk; pk.x = cvtpk(p2[0][0], p2[0][1]); pk.y = cvtpk(p2[0][2], p2[0][3]); pk.z = cvtpk(p2[1][0], p2[1][1]); pk.w = cvtpk(p2[1][2], p2[1][3]);
;                 pb[ks] = __builtin_bit_cast(bf16x8, pk); }
	v_mul_f32_e32 v68, v40, v30
	v_pk_fma_f32 v[30:31], v[40:41], v[30:31], v[68:69] op_sel_hi:[1,1,0]
	v_pk_mov_b32 v[40:41], v[26:27], v[16:17] op_sel:[1,0]
	v_lshlrev_b32_e32 v30, 16, v19
	v_mul_f32_e32 v72, v42, v30
	v_and_b32_e32 v30, 0xffff0000, v19
	v_mul_f32_e32 v37, v43, v30
	v_mul_f32_e32 v30, v33, v49
	v_mov_b32_e32 v68, v34
	v_mov_b32_e32 v69, v28
	v_and_b32_e32 v41, 0xffff0000, v41
	v_and_b32_e32 v40, 0xffff0000, v40
	v_mov_b32_e32 v28, v35
	v_pk_fma_f32 v[32:33], v[32:33], v[48:49], v[30:31] op_sel_hi:[1,1,0]
	v_pk_add_f32 v[34:35], v[44:45], v[44:45] op_sel:[0,1] op_sel_hi:[1,0]
	v_lshlrev_b32_e32 v43, 16, v16
	v_lshlrev_b32_e32 v42, 16, v27
	v_pk_mul_f32 v[28:29], v[28:29], v[40:41]
	v_mov_b32_e32 v33, v70
	v_mov_b32_e32 v35, v71
	v_pk_fma_f32 v[28:29], v[68:69], v[42:43], v[28:29]
	v_pk_add_f32 v[32:33], v[32:33], v[34:35]
	v_mov_b32_e32 v30, v3
	v_pk_add_f32 v[28:29], v[28:29], v[32:33]
	s_nop 0
	v_pk_add_f32 v[28:29], v[28:29], v[30:31]
	v_mul_f32_e32 v30, v39, v51
	v_pk_fma_f32 v[30:31], v[38:39], v[50:51], v[30:31] op_sel_hi:[1,1,0]
	s_nop 0
	v_mov_b32_e32 v31, v72
	v_pk_add_f32 v[30:31], v[30:31], v[36:37]
	v_lshlrev_b32_e32 v36, 16, v12
	v_pk_add_f32 v[28:29], v[30:31], v[28:29]
	s_nop 0
	v_pk_add_f32 v[68:69], v[28:29], v[28:29] op_sel:[0,1] op_sel_hi:[1,0]
	ds_read_b128 v[28:31], v47 offset:384
	ds_read_b128 v[32:35], v47 offset:400
	s_waitcnt lgkmcnt(1)
	v_mul_f32_e32 v72, v28, v36
	v_and_b32_e32 v28, 0xffff0000, v12
	v_mul_f32_e32 v78, v29, v28
	v_and_b32_e32 v29, 0xffff0000, v13
	v_lshlrev_b32_e32 v28, 16, v13
	v_mul_f32_e32 v36, v31, v29
	v_pk_fma_f32 v[76:77], v[30:31], v[28:29], v[36:37] op_sel_hi:[1,1,0]
	v_and_b32_e32 v29, 0xffff0000, v14
	v_lshlrev_b32_e32 v28, 16, v14
	s_waitcnt lgkmcnt(0)
	v_mul_f32_e32 v30, v33, v29
	v_pk_fma_f32 v[74:75], v[32:33], v[28:29], v[30:31] op_sel_hi:[1,1,0]
	v_and_b32_e32 v29, 0xffff0000, v15
	v_lshlrev_b32_e32 v28, 16, v15
	v_mul_f32_e32 v30, v35, v29
	v_pk_fma_f32 v[70:71], v[34:35], v[28:29], v[30:31] op_sel_hi:[1,1,0]
	v_mfma_f32_16x16x32_bf16 v[28:31], v[214:217], v[24:27], 0
	v_mfma_f32_16x16x32_bf16 v[28:31], v[218:221], v[20:23], v[28:31]
	v_mfma_f32_16x16x32_bf16 v[28:31], v[222:225], v[16:19], v[28:31]
	v_mfma_f32_16x16x32_bf16 v[28:31], v[226:229], v[12:15], v[28:31]
	ds_read_b128 v[214:217], v170 offset:21888
	ds_read_b128 v[218:221], v170 offset:21952
	ds_read_b128 v[222:225], v170 offset:26112
	ds_read_b128 v[226:229], v170 offset:26176
	ds_read_b128 v[32:35], v164
	ds_read_b128 v[36:39], v165
	s_waitcnt lgkmcnt(0)
	v_sub_f32_e32 v36, v2, v36
	v_sub_f32_e64 v32, v32, |v36|
	v_sub_f32_e32 v36, v2, v37
	v_sub_f32_e64 v33, v33, |v36|
	v_sub_f32_e32 v32, v32, v102
	v_sub_f32_e32 v33, v33, v102
	v_mul_f32_e32 v32, 0x3fb8aa3b, v32
	v_mul_f32_e32 v33, 0x3fb8aa3b, v33
	v_exp_f32_e32 v32, v32
	v_exp_f32_e32 v33, v33
	s_nop 0
	v_pk_mul_f32 v[40:41], v[28:29], v[32:33]
	s_nop 0
	v_add_f32_e32 v28, 0, v40
	v_add_f32_e32 v32, v41, v28
	v_sub_f32_e32 v28, v2, v38
	v_sub_f32_e32 v29, v2, v39
	v_sub_f32_e64 v28, v34, |v28|
	v_sub_f32_e64 v29, v35, |v29|
	v_sub_f32_e32 v28, v28, v102
	v_sub_f32_e32 v29, v29, v102
	v_mul_f32_e32 v28, 0x3fb8aa3b, v28
	v_mul_f32_e32 v29, 0x3fb8aa3b, v29
	v_exp_f32_e32 v28, v28
	v_exp_f32_e32 v29, v29
	s_nop 0
	v_pk_mul_f32 v[42:43], v[30:31], v[28:29]
	s_nop 0
	v_add_f32_e32 v28, v42, v32
	v_add_f32_e32 v44, v43, v28
	v_mfma_f32_16x16x32_bf16 v[28:31], v[230:233], v[24:27], 0
	v_mfma_f32_16x16x32_bf16 v[28:31], v[234:237], v[20:23], v[28:31]
	v_mfma_f32_16x16x32_bf16 v[28:31], v[214:217], v[16:19], v[28:31]
	v_mfma_f32_16x16x32_bf16 v[28:31], v[218:221], v[12:15], v[28:31]
	ds_read_b128 v[230:233], v170 offset:26240
	ds_read_b128 v[234:237], v170 offset:26304
	ds_read_b128 v[214:217], v170 offset:30464
	ds_read_b128 v[218:221], v170 offset:30528
	ds_read_b128 v[32:35], v164 offset:64
	ds_read_b128 v[36:39], v165 offset:64
	s_waitcnt lgkmcnt(0)
	v_sub_f32_e32 v36, v2, v36
	v_sub_f32_e64 v32, v32, |v36|
	v_sub_f32_e32 v36, v2, v37
	v_sub_f32_e64 v33, v33, |v36|
	v_sub_f32_e32 v32, v32, v102
	v_sub_f32_e32 v33, v33, v102
	v_mul_f32_e32 v32, 0x3fb8aa3b, v32
	v_mul_f32_e32 v33, 0x3fb8aa3b, v33
	v_exp_f32_e32 v32, v32
	v_exp_f32_e32 v33, v33
	s_nop 0
	v_pk_mul_f32 v[32:33], v[28:29], v[32:33]
	s_nop 0
	v_add_f32_e32 v28, v44, v32
	v_add_f32_e32 v36, v33, v28
	v_sub_f32_e32 v28, v2, v38
	v_sub_f32_e32 v29, v2, v39
	v_sub_f32_e64 v28, v34, |v28|
	v_sub_f32_e64 v29, v35, |v29|
	v_sub_f32_e32 v28, v28, v102
	v_sub_f32_e32 v29, v29, v102
	v_mul_f32_e32 v28, 0x3fb8aa3b, v28
	v_mul_f32_e32 v29, 0x3fb8aa3b, v29
	v_exp_f32_e32 v28, v28
	v_exp_f32_e32 v29, v29
	s_nop 0
	v_pk_mul_f32 v[34:35], v[30:31], v[28:29]
	s_nop 0
	v_add_f32_e32 v28, v34, v36
	v_add_f32_e32 v47, v35, v28
	v_cvt_pk_bf16_f32 v30, v32, v33
	v_cvt_pk_bf16_f32 v31, v34, v35
	v_mfma_f32_16x16x32_bf16 v[32:35], v[222:225], v[24:27], 0
	v_cvt_pk_bf16_f32 v28, v40, v41
	v_cvt_pk_bf16_f32 v29, v42, v43
	v_mfma_f32_16x16x32_bf16 v[32:35], v[226:229], v[20:23], v[32:35]
	v_mfma_f32_16x16x32_bf16 v[32:35], v[230:233], v[16:19], v[32:35]
	v_mfma_f32_16x16x32_bf16 v[32:35], v[234:237], v[12:15], v[32:35]
	ds_read_b128 v[222:225], v170 offset:30592
	ds_read_b128 v[226:229], v170 offset:30656
	ds_read_b128 v[36:39], v164 offset:128
	ds_read_b128 v[40:43], v165 offset:128
	s_waitcnt lgkmcnt(0)
; #define GAS __attribute__((address_space(1)))
; #define LAS __attribute__((address_space(3)))
; #define MFMA16(a, b, c) __builtin_amdgcn_mfma_f32_16x16x32_bf16((a), (b), (c), 0, 0, 0)
; __device__ __forceinline__ float fexp(float x) { return __builtin_amdgcn_exp2f(x * LOG2E); }
; __device__ __forceinline__ unsigned cvtpk(float lo, float hi) { const f32x2_t v = {lo, hi}; const bf16x2_t b = __builtin_convertvector(v, bf16x2_t); return __builtin_bit_cast(unsigned, b); }
; __device__ __forceinline__ void ml_out_unit(LAS unsigned char* lds, const MixBufs& B, int b, int h, int seg, int tid) {
;     ...
;             for (int ks = 0; ks < 2; ++ks) { f32x4 p2[2];
; #pragma unroll
;                 for (int jj = 0; jj < 2; ++jj) { const int sj = 2 * ks + jj;
;                     f32x4 acc = (f32x4){0.f, 0.f, 0.f, 0.f};
; #pragma unroll
;                     for (int kk = 0; kk < 4; ++kk) acc = MFMA16(frag_row(lds + O_K, GP128, 16 * sj, 32 * kk, lane), qf[kk], acc);
;                     const f32x4 li4 = *(const LAS f32x4*)(LI + 16 * sj + 4 * g), fc4 = *(const LAS f32x4*)(FC + 16 * sj + 4 * g);
; #pragma unroll
;                     for (int i = 0; i < 4; ++i) { p2[jj][i] = acc[i] * fexp(li4[i] - fabsf(fct - fc4[i]) - mt); dsum += p2[jj][i]; } }
;                 v4u pk; pk.x = cvtpk(p2[0][0], p2[0][1]); pk.y = cvtpk(p2[0][2], p2[0][3]); pk.z = cvtpk(p2[1][0], p2[1][1]); pk.w = cvtpk(p2[1][2], p2[1][3]);
;                 pb[ks] = __builtin_bit_cast(bf16x8, pk); }
;             dsum += __shfl_xor(dsum, 16); dsum += __shfl_xor(dsum, 32);
;             __builtin_amdgcn_sched_barrier(0);
;             u32x2 opv[8];
; #pragma unroll
;             for (int vt = 0; vt < 8; ++vt) opv[vt] = *(const GAS u32x2*)(B.PROJ + trow * NPROJ + PC_OP + h * 128 + 16 * vt + 4 * g);
;             f32x4 a1[8];
; #pragma unroll
;             for (int hv = 0; hv < 2; ++hv) {
;                 f32x4 a2[4];
; #pragma unroll
;                 for (int j = 0; j < 4; ++j) a2[j] = (f32x4){0.f, 0.f, 0.f, 0.f};
; #pragma unroll
;                 for (int kk = 0; kk < 4; ++kk)
; #pragma unroll
;                     for (int j = 0; j < 4; ++j) a2[j] = MFMA16(frag_row(CTc, GP128, 16 * (4 * hv + j), 32 * kk, lane), qf[kk], a2[j]);
; #pragma unroll
;                 for (int j = 0; j < 4; ++j) a1[4 * hv + j] = a2[j] * sc;
	v_sub_f32_e32 v40, v2, v40
	v_sub_f32_e64 v36, v36, |v40|
	v_sub_f32_e32 v40, v2, v41
	v_sub_f32_e64 v37, v37, |v40|
	v_sub_f32_e32 v36, v36, v102
	v_sub_f32_e32 v37, v37, v102
	v_mul_f32_e32 v36, 0x3fb8aa3b, v36
	v_mul_f32_e32 v37, 0x3fb8aa3b, v37
	v_exp_f32_e32 v36, v36
	v_exp_f32_e32 v37, v37
	s_nop 0
	v_pk_mul_f32 v[44:45], v[32:33], v[36:37]
	s_nop 0
	v_add_f32_e32 v32, v47, v44
	v_add_f32_e32 v36, v45, v32
	v_sub_f32_e32 v32, v2, v42
	v_sub_f32_e32 v33, v2, v43
	v_sub_f32_e64 v32, v38, |v32|
	v_sub_f32_e64 v33, v39, |v33|
	v_sub_f32_e32 v32, v32, v102
	v_sub_f32_e32 v33, v33, v102
	v_mul_f32_e32 v32, 0x3fb8aa3b, v32
	v_mul_f32_e32 v33, 0x3fb8aa3b, v33
	v_exp_f32_e32 v32, v32
	v_exp_f32_e32 v33, v33
	s_nop 0
	v_pk_mul_f32 v[80:81], v[34:35], v[32:33]
	v_add_f32_e32 v79, v80, v36
	v_mfma_f32_16x16x32_bf16 v[32:35], v[214:217], v[24:27], 0
	v_mfma_f32_16x16x32_bf16 v[32:35], v[218:221], v[20:23], v[32:35]
	v_mfma_f32_16x16x32_bf16 v[32:35], v[222:225], v[16:19], v[32:35]
	v_mfma_f32_16x16x32_bf16 v[32:35], v[226:229], v[12:15], v[32:35]
	ds_read_b128 v[36:39], v164 offset:192
	ds_read_b128 v[40:43], v165 offset:192
	s_waitcnt lgkmcnt(0)
	v_sub_f32_e32 v40, v2, v40
	v_sub_f32_e64 v36, v36, |v40|
	v_sub_f32_e32 v40, v2, v41
	v_sub_f32_e64 v37, v37, |v40|
	v_sub_f32_e32 v36, v36, v102
	v_sub_f32_e32 v37, v37, v102
	v_mul_f32_e32 v36, 0x3fb8aa3b, v36
	v_mul_f32_e32 v37, 0x3fb8aa3b, v37
	v_exp_f32_e32 v36, v36
	v_exp_f32_e32 v37, v37
	s_nop 0
	v_pk_mul_f32 v[96:97], v[32:33], v[36:37]
	v_sub_f32_e32 v32, v2, v42
	v_sub_f32_e32 v2, v2, v43
	v_sub_f32_e64 v32, v38, |v32|
	v_sub_f32_e64 v2, v39, |v2|
	v_sub_f32_e32 v32, v32, v102
	v_sub_f32_e32 v2, v2, v102
	v_mul_f32_e32 v32, 0x3fb8aa3b, v32
	v_mul_f32_e32 v2, 0x3fb8aa3b, v2
	v_exp_f32_e32 v32, v32
	v_exp_f32_e32 v33, v2
	v_exp_f32_e32 v2, v46
	v_pk_mul_f32 v[100:101], v[34:35], v[32:33]
	v_cvt_pk_bf16_f32 v32, v44, v45
	v_cvt_pk_bf16_f32 v33, v80, v81
	v_cvt_pk_bf16_f32 v34, v96, v97
	v_cvt_pk_bf16_f32 v35, v100, v101
	v_add_u32_e32 v69, s4, v170
	s_waitcnt lgkmcnt(0)
	ds_read_b128 v[214:217], v69
	ds_read_b128 v[218:221], v69 offset:4352
	ds_read_b128 v[222:225], v69 offset:8704
	ds_read_b128 v[226:229], v69 offset:13056
	ds_read_b128 v[230:233], v69 offset:64
	ds_read_b128 v[234:237], v69 offset:4416
	s_waitcnt lgkmcnt(5)
	v_mfma_f32_16x16x32_bf16 v[36:39], v[214:217], v[24:27], 0
	ds_read_b128 v[214:217], v69 offset:8768
	s_waitcnt lgkmcnt(5)
	v_mfma_f32_16x16x32_bf16 v[40:43], v[218:221], v[24:27], 0
	ds_read_b128 v[218:221], v69 offset:13120
	s_waitcnt lgkmcnt(5)
	v_mfma_f32_16x16x32_bf16 v[48:51], v[222:225], v[24:27], 0
	ds_read_b128 v[222:225], v69 offset:128
	s_waitcnt lgkmcnt(5)
	v_mfma_f32_16x16x32_bf16 v[44:47], v[226:229], v[24:27], 0
	ds_read_b128 v[226:229], v69 offset:4480
	s_waitcnt lgkmcnt(5)
	v_mfma_f32_16x16x32_bf16 v[36:39], v[230:233], v[20:23], v[36:39]
	ds_read_b128 v[230:233], v69 offset:8832
	s_waitcnt lgkmcnt(5)
	v_mfma_f32_16x16x32_bf16 v[40:43], v[234:237], v[20:23], v[40:43]
	ds_read_b128 v[234:237], v69 offset:13184
	s_waitcnt lgkmcnt(5)
	v_mfma_f32_16x16x32_bf16 v[48:51], v[214:217], v[20:23], v[48:51]
	ds_read_b128 v[214:217], v69 offset:192
	s_waitcnt lgkmcnt(5)
	v_mfma_f32_16x16x32_bf16 v[44:47], v[218:221], v[20:23], v[44:47]
	ds_read_b128 v[218:221], v69 offset:4544
	s_waitcnt lgkmcnt(5)
	v_mfma_f32_16x16x32_bf16 v[36:39], v[222:225], v[16:19], v[36:39]
	ds_read_b128 v[222:225], v69 offset:8896
	s_waitcnt lgkmcnt(5)
	v_mfma_f32_16x16x32_bf16 v[40:43], v[226:229], v[16:19], v[40:43]
	ds_read_b128 v[226:229], v69 offset:13248
	s_waitcnt lgkmcnt(5)
	v_mfma_f32_16x16x32_bf16 v[48:51], v[230:233], v[16:19], v[48:51]
	s_waitcnt lgkmcnt(4)
	v_mfma_f32_16x16x32_bf16 v[44:47], v[234:237], v[16:19], v[44:47]
	s_waitcnt lgkmcnt(3)
	v_mfma_f32_16x16x32_bf16 v[36:39], v[214:217], v[12:15], v[36:39]
	s_waitcnt lgkmcnt(2)
	v_mfma_f32_16x16x32_bf16 v[40:43], v[218:221], v[12:15], v[40:43]
	s_waitcnt lgkmcnt(1)
	v_mfma_f32_16x16x32_bf16 v[48:51], v[222:225], v[12:15], v[48:51]
	s_waitcnt lgkmcnt(0)
	v_mfma_f32_16x16x32_bf16 v[44:47], v[226:229], v[12:15], v[44:47]
	s_nop 7
	v_pk_mul_f32 v[36:37], v[2:3], v[36:37] op_sel_hi:[0,1]
	v_pk_mul_f32 v[38:39], v[2:3], v[38:39] op_sel_hi:[0,1]
	v_pk_mul_f32 v[40:41], v[2:3], v[40:41] op_sel_hi:[0,1]
	v_pk_mul_f32 v[42:43], v[2:3], v[42:43] op_sel_hi:[0,1]
	v_pk_mul_f32 v[48:49], v[2:3], v[48:49] op_sel_hi:[0,1]
	v_pk_mul_f32 v[50:51], v[2:3], v[50:51] op_sel_hi:[0,1]
	v_pk_mul_f32 v[44:45], v[2:3], v[44:45] op_sel_hi:[0,1]
	v_pk_mul_f32 v[46:47], v[2:3], v[46:47] op_sel_hi:[0,1]
	ds_read_b128 v[214:217], v69 offset:17408
	ds_read_b128 v[218:221], v69 offset:21760
	ds_read_b128 v[222:225], v69 offset:26112
	ds_read_b128 v[226:229], v69 offset:30464
	ds_read_b128 v[230:233], v69 offset:17472
	ds_read_b128 v[234:237], v69 offset:21824
	s_waitcnt lgkmcnt(5)
	v_mfma_f32_16x16x32_bf16 v[104:107], v[214:217], v[24:27], 0
	ds_read_b128 v[214:217], v69 offset:26176
	s_waitcnt lgkmcnt(5)
	v_mfma_f32_16x16x32_bf16 v[108:111], v[218:221], v[24:27], 0
	ds_read_b128 v[218:221], v69 offset:30528
	s_waitcnt lgkmcnt(5)
	v_mfma_f32_16x16x32_bf16 v[112:115], v[222:225], v[24:27], 0
	ds_read_b128 v[222:225], v69 offset:17536
	s_waitcnt lgkmcnt(5)
	v_mfma_f32_16x16x32_bf16 v[116:119], v[226:229], v[24:27], 0
	ds_read_b128 v[226:229], v69 offset:21888
	s_waitcnt lgkmcnt(5)
	v_mfma_f32_16x16x32_bf16 v[104:107], v[230:233], v[20:23], v[104:107]
	ds_read_b128 v[230:233], v69 offset:26240
	s_waitcnt lgkmcnt(5)
	v_mfma_f32_16x16x32_bf16 v[108:111], v[234:237], v[20:23], v[108:111]
	ds_read_b128 v[234:237], v69 offset:30592
	s_waitcnt lgkmcnt(5)
; #define MFMA16(a, b, c) __builtin_amdgcn_mfma_f32_16x16x32_bf16((a), (b), (c), 0, 0, 0)
; __device__ __forceinline__ float fexp(float x) { return __builtin_amdgcn_exp2f(x * LOG2E); }
; __device__ __forceinline__ void ml_out_unit(LAS unsigned char* lds, const MixBufs& B, int b, int h, int seg, int tid) {
;     ...
;             for (int hv = 0; hv < 2; ++hv) {
;                 f32x4 a2[4];
; #pragma unroll
;                 for (int j = 0; j < 4; ++j) a2[j] = (f32x4){0.f, 0.f, 0.f, 0.f};
; #pragma unroll
;                 for (int kk = 0; kk < 4; ++kk)
; #pragma unroll
;                     for (int j = 0; j < 4; ++j) a2[j] = MFMA16(frag_row(CTc, GP128, 16 * (4 * hv + j), 32 * kk, lane), qf[kk], a2[j]);
; #pragma unroll
;                 for (int j = 0; j < 4; ++j) a1[4 * hv + j] = a2[j] * sc;
;                 __builtin_amdgcn_sched_barrier(0); }
; #pragma unroll
;             for (int ks = 0; ks < 2; ++ks)
; #pragma unroll
;                 for (int vt = 0; vt < 8; ++vt) a1[vt] = MFMA16(frag_tr_perm(lds + O_V, GP128, 32 * ks, 16 * vt, lane), pb[ks], a1[vt]);
;             float den = dsum + sc * qn;
;             den = fmaxf(fabsf(den), fexp(-mt));
;             const float rden = 1.f / den;
	v_mfma_f32_16x16x32_bf16 v[112:115], v[214:217], v[20:23], v[112:115]
	ds_read_b128 v[214:217], v69 offset:17600
	s_waitcnt lgkmcnt(5)
	v_mfma_f32_16x16x32_bf16 v[116:119], v[218:221], v[20:23], v[116:119]
	ds_read_b128 v[218:221], v69 offset:21952
	s_waitcnt lgkmcnt(5)
	v_mfma_f32_16x16x32_bf16 v[104:107], v[222:225], v[16:19], v[104:107]
	ds_read_b128 v[222:225], v69 offset:26304
	s_waitcnt lgkmcnt(5)
	v_mfma_f32_16x16x32_bf16 v[108:111], v[226:229], v[16:19], v[108:111]
	ds_read_b128 v[226:229], v69 offset:30656
	s_waitcnt lgkmcnt(5)
	v_mfma_f32_16x16x32_bf16 v[112:115], v[230:233], v[16:19], v[112:115]
	s_waitcnt lgkmcnt(4)
	v_mfma_f32_16x16x32_bf16 v[116:119], v[234:237], v[16:19], v[116:119]
	s_waitcnt lgkmcnt(3)
	v_mfma_f32_16x16x32_bf16 v[104:107], v[214:217], v[12:15], v[104:107]
	s_waitcnt lgkmcnt(2)
	v_mfma_f32_16x16x32_bf16 v[108:111], v[218:221], v[12:15], v[108:111]
	s_waitcnt lgkmcnt(1)
	v_mfma_f32_16x16x32_bf16 v[112:115], v[222:225], v[12:15], v[112:115]
	s_waitcnt lgkmcnt(0)
	v_mfma_f32_16x16x32_bf16 v[116:119], v[226:229], v[12:15], v[116:119]
	s_nop 7
	v_pk_mul_f32 v[16:17], v[2:3], v[104:105] op_sel_hi:[0,1]
	v_pk_mul_f32 v[18:19], v[2:3], v[106:107] op_sel_hi:[0,1]
	v_pk_mul_f32 v[20:21], v[2:3], v[108:109] op_sel_hi:[0,1]
	v_pk_mul_f32 v[22:23], v[2:3], v[110:111] op_sel_hi:[0,1]
	v_pk_mul_f32 v[24:25], v[2:3], v[112:113] op_sel_hi:[0,1]
	v_pk_mul_f32 v[26:27], v[2:3], v[114:115] op_sel_hi:[0,1]
	v_pk_mul_f32 v[12:13], v[2:3], v[116:117] op_sel_hi:[0,1]
	v_pk_mul_f32 v[14:15], v[2:3], v[118:119] op_sel_hi:[0,1]
	ds_read_b64_tr_b16 v[104:105], v167 offset:34816
	ds_read_b64_tr_b16 v[106:107], v167 offset:39168
	ds_read_b64_tr_b16 v[110:111], v167 offset:39200
	ds_read_b64_tr_b16 v[108:109], v167 offset:34848
	ds_read_b64_tr_b16 v[112:113], v167 offset:34880
	ds_read_b64_tr_b16 v[116:117], v167 offset:34912
	ds_read_b64_tr_b16 v[114:115], v167 offset:39232
	ds_read_b64_tr_b16 v[118:119], v167 offset:39264
	s_waitcnt lgkmcnt(6)
	v_mfma_f32_16x16x32_bf16 v[36:39], v[104:107], v[28:31], v[36:39]
	v_mov_b32_e32 v73, v81
	v_mov_b32_e32 v77, v96
	v_mov_b32_e32 v75, v97
	s_waitcnt lgkmcnt(4)
	v_mfma_f32_16x16x32_bf16 v[104:107], v[108:111], v[28:31], v[40:43]
	s_nop 2
	ds_read_b64_tr_b16 v[40:41], v167 offset:34944
	ds_read_b64_tr_b16 v[42:43], v167 offset:39296
	ds_read_b64_tr_b16 v[110:111], v167 offset:39328
	v_mov_b32_e32 v71, v100
	v_mov_b32_e32 v69, v101
	s_waitcnt lgkmcnt(4)
	v_mfma_f32_16x16x32_bf16 v[48:51], v[112:115], v[28:31], v[48:51]
	s_xor_b32 s7, s7, 1
	s_add_u32 s14, s14, 0x10000
	s_addc_u32 s15, s15, 0
	s_waitcnt lgkmcnt(3)
	v_mfma_f32_16x16x32_bf16 v[44:47], v[116:119], v[28:31], v[44:47]
	ds_read_b64_tr_b16 v[108:109], v167 offset:34976
	ds_read_b64_tr_b16 v[112:113], v167 offset:35008
	ds_read_b64_tr_b16 v[116:117], v167 offset:35040
	ds_read_b64_tr_b16 v[114:115], v167 offset:39360
	ds_read_b64_tr_b16 v[118:119], v167 offset:39392
	s_add_u32 s12, s12, 64
	s_addc_u32 s13, s13, 0
	s_waitcnt lgkmcnt(6)
	v_mfma_f32_16x16x32_bf16 v[16:19], v[40:43], v[28:31], v[16:19]
	ds_read_b64_tr_b16 v[40:41], v167 offset:43520
	s_add_i32 s20, s20, 1
	s_add_i32 s26, s26, 8
	s_waitcnt lgkmcnt(5)
	v_mfma_f32_16x16x32_bf16 v[20:23], v[108:111], v[28:31], v[20:23]
	s_cmp_eq_u32 s14, 0x80000
	s_waitcnt lgkmcnt(2)
	v_mfma_f32_16x16x32_bf16 v[108:111], v[112:115], v[28:31], v[24:27]
	ds_read_b64_tr_b16 v[42:43], v167 offset:47872
	s_nop 1
	ds_read_b64_tr_b16 v[26:27], v167 offset:47904
	s_waitcnt lgkmcnt(3)
	v_mfma_f32_16x16x32_bf16 v[112:115], v[116:119], v[28:31], v[12:15]
	ds_read_b64_tr_b16 v[24:25], v167 offset:43552
	s_nop 1
	ds_read_b64_tr_b16 v[12:13], v167 offset:43584
	ds_read_b64_tr_b16 v[116:117], v167 offset:43616
	ds_read_b64_tr_b16 v[14:15], v167 offset:47936
	ds_read_b64_tr_b16 v[118:119], v167 offset:47968
	ds_read_b64_tr_b16 v[120:121], v167 offset:43648
	ds_read_b64_tr_b16 v[124:125], v167 offset:43680
	ds_read_b64_tr_b16 v[128:129], v167 offset:43712
	ds_read_b64_tr_b16 v[132:133], v167 offset:43744
	ds_read_b64_tr_b16 v[122:123], v167 offset:48000
	ds_read_b64_tr_b16 v[126:127], v167 offset:48032
	ds_read_b64_tr_b16 v[130:131], v167 offset:48064
	ds_read_b64_tr_b16 v[134:135], v167 offset:48096
	s_waitcnt lgkmcnt(14)
	v_mfma_f32_16x16x32_bf16 v[40:43], v[40:43], v[32:35], v[36:39]
	s_waitcnt lgkmcnt(9)
	v_mfma_f32_16x16x32_bf16 v[36:39], v[12:15], v[32:35], v[48:51]
	v_add_f32_e64 v12, v72, v78
	v_add_f32_e64 v13, v73, v79
	v_pk_add_f32 v[12:13], v[12:13], v[76:77]
	v_mfma_f32_16x16x32_bf16 v[28:31], v[24:27], v[32:35], v[104:107]
	s_waitcnt lgkmcnt(8)
	v_mfma_f32_16x16x32_bf16 v[24:27], v[116:119], v[32:35], v[44:47]
	s_nop 2
	v_add_f32_e64 v44, v74, v12
	v_add_f32_e64 v45, v75, v13
	s_waitcnt lgkmcnt(3)
	v_mfma_f32_16x16x32_bf16 v[12:15], v[120:123], v[32:35], v[16:19]
	s_nop 2
	v_add_f32_e64 v16, v70, v44
	v_add_f32_e64 v17, v71, v45
	v_mul_f32_e32 v44, 0xbfb8aa3b, v102
	v_pk_add_f32 v[16:17], v[68:69], v[16:17]
	ds_bpermute_b32 v18, v200, v16
	ds_bpermute_b32 v19, v200, v17
	v_exp_f32_e32 v48, v44
	s_waitcnt lgkmcnt(4)
	v_mfma_f32_16x16x32_bf16 v[20:23], v[124:127], v[32:35], v[20:23]
	s_waitcnt lgkmcnt(0)
	v_pk_add_f32 v[16:17], v[16:17], v[18:19]
	ds_bpermute_b32 v18, v199, v16
	ds_bpermute_b32 v19, v199, v17
	v_mfma_f32_16x16x32_bf16 v[44:47], v[128:131], v[32:35], v[108:111]
	s_waitcnt lgkmcnt(0)
	v_pk_add_f32 v[16:17], v[16:17], v[18:19]
	s_nop 0
	v_fmac_f32_e32 v17, v2, v16
	v_max_f32_e64 v2, |v17|, v48
	v_div_scale_f32 v48, s[4:5], v2, v2, 1.0
	v_rcp_f32_e32 v49, v48
	v_mfma_f32_16x16x32_bf16 v[16:19], v[132:135], v[32:35], v[112:115]
	s_waitcnt vmcnt(7)
; __device__ __forceinline__ float fexp(float x) { return __builtin_amdgcn_exp2f(x * LOG2E); }
; __device__ __forceinline__ float fsigmoid(float x) { return __builtin_amdgcn_rcpf(1.f + __builtin_amdgcn_exp2f(-LOG2E * x)); }
; __device__ __forceinline__ f32x4 bf4_to_f32(u32x2 w) { return (f32x4){bflo(w.x), bfhi(w.x), bflo(w.y), bfhi(w.y)}; }
; __device__ __forceinline__ void ml_out_unit(LAS unsigned char* lds, const MixBufs& B, int b, int h, int seg, int tid) {
;     ...
;             float den = dsum + sc * qn;
;             den = fmaxf(fabsf(den), fexp(-mt));
;             const float rden = 1.f / den;
;             float s1 = 0.f, s2 = 0.f;
; #pragma unroll
;             for (int vt = 0; vt < 8; ++vt) { const f32x4 op = bf4_to_f32(opv[vt]);
; #pragma unroll
;                 for (int i = 0; i < 4; ++i) { const float x = a1[vt][i] * rden * fsigmoid(op[i]); a1[vt][i] = x; s1 += x; s2 += x * x; } }
	v_and_b32_e32 v35, 0xffff0000, v99
	s_brev_b32 s4, 60
	v_fma_f32 v32, -v48, v49, 1.0
	v_fmac_f32_e32 v49, v32, v49
	v_div_scale_f32 v32, vcc, 1.0, v2, 1.0
	v_mul_f32_e32 v33, v32, v49
	v_fma_f32 v34, -v48, v33, v32
	v_fmac_f32_e32 v33, v34, v49
	v_fma_f32 v32, -v48, v33, v32
	v_div_fmas_f32 v32, v32, v49, v33
	v_div_fixup_f32 v2, v32, v2, 1.0
	v_lshlrev_b32_e32 v32, 16, v98
	v_and_b32_e32 v33, 0xffff0000, v98
	v_mul_f32_e32 v32, 0xbfb8aa3b, v32
	v_exp_f32_e32 v32, v32
	v_mul_f32_e32 v33, 0xbfb8aa3b, v33
	v_exp_f32_e32 v33, v33
	v_lshlrev_b32_e32 v34, 16, v99
	v_add_f32_e32 v32, 1.0, v32
	v_rcp_f32_e32 v48, v32
	v_add_f32_e32 v32, 1.0, v33
	v_mul_f32_e32 v33, 0xbfb8aa3b, v34
	v_exp_f32_e32 v33, v33
	v_mul_f32_e32 v34, 0xbfb8aa3b, v35
	v_exp_f32_e32 v34, v34
	v_rcp_f32_e32 v49, v32
	v_add_f32_e32 v32, 1.0, v33
	v_rcp_f32_e32 v50, v32
	v_add_f32_e32 v32, 1.0, v34
	v_rcp_f32_e32 v51, v32
	s_waitcnt vmcnt(6)
	v_lshlrev_b32_e32 v32, 16, v94
	v_and_b32_e32 v33, 0xffff0000, v94
	v_mul_f32_e32 v32, 0xbfb8aa3b, v32
	v_exp_f32_e32 v32, v32
	v_mul_f32_e32 v33, 0xbfb8aa3b, v33
	v_exp_f32_e32 v33, v33
	v_lshlrev_b32_e32 v34, 16, v95
	v_add_f32_e32 v32, 1.0, v32
	v_and_b32_e32 v35, 0xffff0000, v95
	v_rcp_f32_e32 v68, v32
	v_add_f32_e32 v32, 1.0, v33
	v_mul_f32_e32 v33, 0xbfb8aa3b, v34
	v_exp_f32_e32 v33, v33
	v_mul_f32_e32 v34, 0xbfb8aa3b, v35
	v_exp_f32_e32 v34, v34
	v_rcp_f32_e32 v69, v32
	v_add_f32_e32 v32, 1.0, v33
	v_rcp_f32_e32 v70, v32
	v_add_f32_e32 v32, 1.0, v34
	v_rcp_f32_e32 v71, v32
	s_waitcnt vmcnt(5)
	v_lshlrev_b32_e32 v32, 16, v92
	v_and_b32_e32 v33, 0xffff0000, v92
	v_mul_f32_e32 v32, 0xbfb8aa3b, v32
	v_exp_f32_e32 v32, v32
	v_mul_f32_e32 v33, 0xbfb8aa3b, v33
	v_exp_f32_e32 v33, v33
	v_lshlrev_b32_e32 v34, 16, v93
	v_add_f32_e32 v32, 1.0, v32
	v_and_b32_e32 v35, 0xffff0000, v93
	v_rcp_f32_e32 v72, v32
	v_add_f32_e32 v32, 1.0, v33
	v_mul_f32_e32 v33, 0xbfb8aa3b, v34
	v_exp_f32_e32 v33, v33
	v_mul_f32_e32 v34, 0xbfb8aa3b, v35
	v_exp_f32_e32 v34, v34
	v_rcp_f32_e32 v73, v32
	v_add_f32_e32 v32, 1.0, v33
	v_rcp_f32_e32 v74, v32
	v_add_f32_e32 v32, 1.0, v34
	v_rcp_f32_e32 v75, v32
	s_waitcnt vmcnt(4)
	v_lshlrev_b32_e32 v32, 16, v90
	v_and_b32_e32 v33, 0xffff0000, v90
	v_mul_f32_e32 v32, 0xbfb8aa3b, v32
	v_exp_f32_e32 v32, v32
	v_mul_f32_e32 v33, 0xbfb8aa3b, v33
	v_exp_f32_e32 v33, v33
	v_lshlrev_b32_e32 v34, 16, v91
	v_add_f32_e32 v32, 1.0, v32
	v_and_b32_e32 v35, 0xffff0000, v91
	v_rcp_f32_e32 v76, v32
	v_add_f32_e32 v32, 1.0, v33
	v_mul_f32_e32 v33, 0xbfb8aa3b, v34
	v_exp_f32_e32 v33, v33
	v_mul_f32_e32 v34, 0xbfb8aa3b, v35
	v_exp_f32_e32 v34, v34
	v_rcp_f32_e32 v77, v32
	v_add_f32_e32 v32, 1.0, v33
	v_rcp_f32_e32 v78, v32
	v_add_f32_e32 v32, 1.0, v34
	v_rcp_f32_e32 v79, v32
	s_waitcnt vmcnt(3)
	v_lshlrev_b32_e32 v32, 16, v88
	v_and_b32_e32 v33, 0xffff0000, v88
	v_mul_f32_e32 v32, 0xbfb8aa3b, v32
	v_exp_f32_e32 v32, v32
	v_mul_f32_e32 v33, 0xbfb8aa3b, v33
	v_exp_f32_e32 v33, v33
	v_pk_mul_f32 v[94:95], v[2:3], v[20:21] op_sel_hi:[0,1]
	s_waitcnt vmcnt(1)
	v_lshlrev_b32_e32 v20, 16, v84
	v_lshlrev_b32_e32 v34, 16, v89
	v_add_f32_e32 v32, 1.0, v32
	v_and_b32_e32 v21, 0xffff0000, v84
	v_mul_f32_e32 v20, 0xbfb8aa3b, v20
	v_and_b32_e32 v35, 0xffff0000, v89
	v_rcp_f32_e32 v80, v32
	v_add_f32_e32 v32, 1.0, v33
	v_mul_f32_e32 v33, 0xbfb8aa3b, v34
	v_exp_f32_e32 v20, v20
	v_mul_f32_e32 v21, 0xbfb8aa3b, v21
	v_exp_f32_e32 v33, v33
	v_mul_f32_e32 v34, 0xbfb8aa3b, v35
	v_exp_f32_e32 v21, v21
	v_exp_f32_e32 v34, v34
	v_add_f32_e32 v20, 1.0, v20
	v_rcp_f32_e32 v81, v32
	v_add_f32_e32 v32, 1.0, v33
	v_pk_mul_f32 v[92:93], v[2:3], v[22:23] op_sel_hi:[0,1]
	v_lshlrev_b32_e32 v22, 16, v85
	v_rcp_f32_e32 v84, v20
	v_add_f32_e32 v20, 1.0, v21
	v_rcp_f32_e32 v88, v32
	v_add_f32_e32 v32, 1.0, v34
	v_and_b32_e32 v23, 0xffff0000, v85
	v_rcp_f32_e32 v85, v20
	v_mul_f32_e32 v20, 0xbfb8aa3b, v22
	v_rcp_f32_e32 v89, v32
	v_lshlrev_b32_e32 v32, 16, v86
	v_exp_f32_e32 v20, v20
	v_mul_f32_e32 v21, 0xbfb8aa3b, v23
	v_and_b32_e32 v33, 0xffff0000, v86
	v_mul_f32_e32 v32, 0xbfb8aa3b, v32
	v_exp_f32_e32 v21, v21
	v_exp_f32_e32 v32, v32
	v_mul_f32_e32 v33, 0xbfb8aa3b, v33
	v_exp_f32_e32 v33, v33
	v_add_f32_e32 v20, 1.0, v20
	v_rcp_f32_e32 v98, v20
	v_add_f32_e32 v20, 1.0, v21
	v_lshlrev_b32_e32 v34, 16, v87
	v_add_f32_e32 v32, 1.0, v32
	v_rcp_f32_e32 v99, v20
	s_waitcnt vmcnt(0)
	v_lshlrev_b32_e32 v20, 16, v82
	v_lshlrev_b32_e32 v22, 16, v83
	v_and_b32_e32 v35, 0xffff0000, v87
	v_rcp_f32_e32 v86, v32
	v_add_f32_e32 v32, 1.0, v33
	v_mul_f32_e32 v33, 0xbfb8aa3b, v34
	v_and_b32_e32 v21, 0xffff0000, v82
	v_mul_f32_e32 v20, 0xbfb8aa3b, v20
	v_and_b32_e32 v23, 0xffff0000, v83
	v_pk_mul_f32 v[102:103], v[2:3], v[16:17] op_sel_hi:[0,1]
	v_mul_f32_e32 v16, 0xbfb8aa3b, v22
	v_exp_f32_e32 v33, v33
	v_mul_f32_e32 v34, 0xbfb8aa3b, v35
	v_exp_f32_e32 v20, v20
	v_mul_f32_e32 v21, 0xbfb8aa3b, v21
	v_exp_f32_e32 v16, v16
	v_mul_f32_e32 v17, 0xbfb8aa3b, v23
	v_exp_f32_e32 v34, v34
	v_exp_f32_e32 v21, v21
	v_exp_f32_e32 v17, v17
	v_rcp_f32_e32 v87, v32
	v_add_f32_e32 v32, 1.0, v33
	v_add_f32_e32 v20, 1.0, v20
	v_add_f32_e32 v16, 1.0, v16
	v_rcp_f32_e32 v90, v32
	v_add_f32_e32 v32, 1.0, v34
	v_rcp_f32_e32 v82, v20
	v_add_f32_e32 v20, 1.0, v21
	v_rcp_f32_e32 v104, v16
	v_add_f32_e32 v16, 1.0, v17
	v_rcp_f32_e32 v91, v32
	v_rcp_f32_e32 v83, v20
	v_rcp_f32_e32 v105, v16
	v_pk_mul_f32 v[106:107], v[2:3], v[18:19] op_sel_hi:[0,1]
	ds_read_b64 v[32:33], v168 offset:52224
	ds_read_b128 v[16:19], v171
	ds_read_b128 v[20:23], v172
	v_pk_mul_f32 v[114:115], v[2:3], v[40:41] op_sel_hi:[0,1]
	v_pk_mul_f32 v[40:41], v[48:49], v[114:115]
	v_pk_mul_f32 v[108:109], v[2:3], v[42:43] op_sel_hi:[0,1]
	s_waitcnt lgkmcnt(2)
; #define LAS __attribute__((address_space(3)))
; __device__ __forceinline__ float fsigmoid(float x) { return __builtin_amdgcn_rcpf(1.f + __builtin_amdgcn_exp2f(-LOG2E * x)); }
; __device__ __forceinline__ f32x4 bf4_to_f32(u32x2 w) { return (f32x4){bflo(w.x), bfhi(w.x), bflo(w.y), bfhi(w.y)}; }
; __device__ __forceinline__ void ml_out_unit(LAS unsigned char* lds, const MixBufs& B, int b, int h, int seg, int tid) {
;     ...
;             for (int vt = 0; vt < 8; ++vt) { const f32x4 op = bf4_to_f32(opv[vt]);
; #pragma unroll
;                 for (int i = 0; i < 4; ++i) { const float x = a1[vt][i] * rden * fsigmoid(op[i]); a1[vt][i] = x; s1 += x; s2 += x * x; } }
;             s1 += __shfl_xor(s1, 16); s1 += __shfl_xor(s1, 32); s2 += __shfl_xor(s2, 16); s2 += __shfl_xor(s2, 32);
;             const float mu = s1 * (1.f / 128.f), var = s2 * (1.f / 128.f) - mu * mu, rstd = 1.f / sqrtf(fmaxf(var, 0.f) + EPS);
; #pragma unroll
;             for (int vt = 0; vt < 8; ++vt) { const int cl = 16 * vt + 4 * g; const f32x4 xc = bf4_to_f32(*(const LAS u32x2*)(lds + O_XC + (16 * ti + c) * GP128 + cl * 2)), gn = *(const LAS f32x4*)(GN + cl), sk = *(const LAS f32x4*)(SK + cl);
	v_lshlrev_b32_e32 v112, 16, v33
	v_and_b32_e32 v113, 0xffff0000, v33
	v_add_f32_e32 v33, 0, v40
	v_pk_mul_f32 v[96:97], v[2:3], v[44:45] op_sel_hi:[0,1]
	v_pk_mul_f32 v[34:35], v[50:51], v[108:109]
	ds_read_b64 v[44:45], v169 offset:52224
	ds_read_b64 v[202:203], v192 offset:52224
	ds_read_b64 v[204:205], v193 offset:52224
	v_add_f32_e32 v33, v41, v33
	v_mul_f32_e32 v42, v41, v41
	v_pk_fma_f32 v[40:41], v[40:41], v[40:41], v[42:43] op_sel_hi:[1,1,0]
	v_add_f32_e32 v42, v34, v33
	v_pk_mul_f32 v[122:123], v[2:3], v[28:29] op_sel_hi:[0,1]
	v_lshlrev_b32_e32 v120, 16, v32
	v_and_b32_e32 v121, 0xffff0000, v32
	v_pk_fma_f32 v[32:33], v[34:35], v[34:35], v[40:41]
	v_add_f32_e32 v124, v35, v42
	v_mul_f32_e32 v34, v35, v35
	v_pk_mul_f32 v[28:29], v[68:69], v[122:123]
	v_pk_mul_f32 v[100:101], v[2:3], v[46:47] op_sel_hi:[0,1]
	v_pk_add_f32 v[46:47], v[34:35], v[32:33] op_sel_hi:[0,1]
	v_pk_mul_f32 v[118:119], v[2:3], v[30:31] op_sel_hi:[0,1]
	s_waitcnt lgkmcnt(2)
	v_lshlrev_b32_e32 v116, 16, v45
	v_and_b32_e32 v117, 0xffff0000, v45
	v_add_f32_e32 v45, v28, v124
	v_pk_mul_f32 v[30:31], v[70:71], v[118:119]
	v_pk_fma_f32 v[46:47], v[28:29], v[28:29], v[46:47]
	v_add_f32_e32 v45, v29, v45
	v_mul_f32_e32 v28, v29, v29
	v_pk_add_f32 v[28:29], v[28:29], v[46:47] op_sel_hi:[0,1]
	v_lshlrev_b32_e32 v126, 16, v44
	v_and_b32_e32 v127, 0xffff0000, v44
	v_add_f32_e32 v44, v30, v45
	v_pk_mul_f32 v[36:37], v[2:3], v[36:37] op_sel_hi:[0,1]
	v_pk_fma_f32 v[28:29], v[30:31], v[30:31], v[28:29]
	v_add_f32_e32 v186, v31, v44
	v_mul_f32_e32 v30, v31, v31
	v_pk_mul_f32 v[210:211], v[72:73], v[36:37]
	v_pk_add_f32 v[128:129], v[30:31], v[28:29] op_sel_hi:[0,1]
	v_pk_mul_f32 v[124:125], v[2:3], v[38:39] op_sel_hi:[0,1]
	v_add_f32_e32 v186, v210, v186
	v_pk_mul_f32 v[208:209], v[74:75], v[124:125]
	v_pk_fma_f32 v[128:129], v[210:211], v[210:211], v[128:129]
	v_add_f32_e32 v201, v211, v186
	v_mul_f32_e32 v186, v211, v211
	v_pk_add_f32 v[210:211], v[186:187], v[128:129] op_sel_hi:[0,1]
	v_add_f32_e32 v186, v208, v201
	v_pk_mul_f32 v[24:25], v[2:3], v[24:25] op_sel_hi:[0,1]
	s_waitcnt lgkmcnt(1)
	v_lshlrev_b32_e32 v38, 16, v203
	v_and_b32_e32 v39, 0xffff0000, v203
	v_lshlrev_b32_e32 v128, 16, v202
	v_and_b32_e32 v129, 0xffff0000, v202
	v_pk_fma_f32 v[202:203], v[208:209], v[208:209], v[210:211]
	v_add_f32_e32 v201, v209, v186
	v_mul_f32_e32 v186, v209, v209
	v_pk_mul_f32 v[210:211], v[76:77], v[24:25]
	v_pk_add_f32 v[202:203], v[186:187], v[202:203] op_sel_hi:[0,1]
	v_pk_mul_f32 v[26:27], v[2:3], v[26:27] op_sel_hi:[0,1]
	v_add_f32_e32 v186, v210, v201
	v_pk_mul_f32 v[208:209], v[78:79], v[26:27]
	v_pk_fma_f32 v[202:203], v[210:211], v[210:211], v[202:203]
	v_add_f32_e32 v201, v211, v186
	v_mul_f32_e32 v186, v211, v211
	v_pk_add_f32 v[202:203], v[186:187], v[202:203] op_sel_hi:[0,1]
	v_add_f32_e32 v186, v208, v201
	v_pk_mul_f32 v[12:13], v[2:3], v[12:13] op_sel_hi:[0,1]
	v_pk_fma_f32 v[202:203], v[208:209], v[208:209], v[202:203]
	v_add_f32_e32 v201, v209, v186
	v_mul_f32_e32 v186, v209, v209
	v_pk_mul_f32 v[212:213], v[80:81], v[12:13]
	v_pk_add_f32 v[202:203], v[186:187], v[202:203] op_sel_hi:[0,1]
	v_pk_mul_f32 v[14:15], v[2:3], v[14:15] op_sel_hi:[0,1]
	v_add_f32_e32 v2, v212, v201
	v_pk_mul_f32 v[208:209], v[88:89], v[14:15]
	v_pk_fma_f32 v[202:203], v[212:213], v[212:213], v[202:203]
	v_add_f32_e32 v186, v213, v2
	v_mul_f32_e32 v2, v213, v213
	v_pk_add_f32 v[202:203], v[2:3], v[202:203] op_sel_hi:[0,1]
	v_add_f32_e32 v2, v208, v186
	v_pk_mul_f32 v[130:131], v[86:87], v[94:95]
	v_pk_fma_f32 v[202:203], v[208:209], v[208:209], v[202:203]
	v_add_f32_e32 v186, v209, v2
	v_mul_f32_e32 v2, v209, v209
	v_mov_b32_e32 v210, v130
	v_mov_b32_e32 v211, v209
	v_pk_add_f32 v[202:203], v[2:3], v[202:203] op_sel_hi:[0,1]
	v_add_f32_e32 v2, v130, v186
	v_pk_mul_f32 v[132:133], v[90:91], v[92:93]
	v_pk_fma_f32 v[202:203], v[210:211], v[210:211], v[202:203]
	v_add_f32_e32 v186, v131, v2
	v_mul_f32_e32 v2, v131, v131
	v_mov_b32_e32 v134, v132
	v_mov_b32_e32 v135, v131
	v_pk_add_f32 v[130:131], v[2:3], v[202:203] op_sel_hi:[0,1]
	v_add_f32_e32 v2, v132, v186
	v_pk_mul_f32 v[136:137], v[84:85], v[96:97]
	v_pk_fma_f32 v[130:131], v[134:135], v[134:135], v[130:131]
	v_add_f32_e32 v132, v133, v2
	v_mul_f32_e32 v2, v133, v133
	v_mov_b32_e32 v140, v136
	v_mov_b32_e32 v141, v133
	v_pk_add_f32 v[130:131], v[2:3], v[130:131] op_sel_hi:[0,1]
	v_add_f32_e32 v2, v136, v132
	v_pk_mul_f32 v[138:139], v[98:99], v[100:101]
	v_pk_fma_f32 v[130:131], v[140:141], v[140:141], v[130:131]
	v_add_f32_e32 v132, v137, v2
	v_mul_f32_e32 v2, v137, v137
	v_mov_b32_e32 v142, v138
	v_mov_b32_e32 v143, v137
	v_pk_add_f32 v[130:131], v[2:3], v[130:131] op_sel_hi:[0,1]
	v_add_f32_e32 v2, v138, v132
	v_pk_mul_f32 v[144:145], v[82:83], v[102:103]
	v_pk_fma_f32 v[130:131], v[142:143], v[142:143], v[130:131]
	v_add_f32_e32 v132, v139, v2
	v_mul_f32_e32 v2, v139, v139
	v_mov_b32_e32 v148, v144
	v_mov_b32_e32 v149, v139
	v_pk_add_f32 v[130:131], v[2:3], v[130:131] op_sel_hi:[0,1]
	v_add_f32_e32 v2, v144, v132
	v_pk_mul_f32 v[146:147], v[104:105], v[106:107]
	v_pk_fma_f32 v[130:131], v[148:149], v[148:149], v[130:131]
	v_add_f32_e32 v132, v145, v2
	v_mul_f32_e32 v2, v145, v145
	v_mov_b32_e32 v150, v146
	v_mov_b32_e32 v151, v145
	v_pk_add_f32 v[130:131], v[2:3], v[130:131] op_sel_hi:[0,1]
	v_pk_fma_f32 v[130:131], v[150:151], v[150:151], v[130:131]
	v_mul_f32_e32 v206, v147, v147
	v_add_f32_e32 v207, v146, v132
	v_mov_b32_e32 v131, v147
	v_pk_add_f32 v[130:131], v[130:131], v[206:207]
	ds_bpermute_b32 v141, v200, v131
	ds_bpermute_b32 v140, v200, v130
	ds_read_b128 v[32:35], v173
	ds_read_b128 v[40:43], v174
	ds_read_b128 v[28:31], v175
	ds_read_b128 v[44:47], v176
	ds_read_b128 v[132:135], v177
	ds_read_b128 v[136:139], v178
	v_lshl_add_u64 v[110:111], s[88:89], 0, v[66:67]
	s_waitcnt lgkmcnt(6)
; #define LAS __attribute__((address_space(3)))
; __device__ __forceinline__ f32x4 bf4_to_f32(u32x2 w) { return (f32x4){bflo(w.x), bfhi(w.x), bflo(w.y), bfhi(w.y)}; }
; __device__ __forceinline__ void ml_out_unit(LAS unsigned char* lds, const MixBufs& B, int b, int h, int seg, int tid) {
;     ...
;             s1 += __shfl_xor(s1, 16); s1 += __shfl_xor(s1, 32); s2 += __shfl_xor(s2, 16); s2 += __shfl_xor(s2, 32);
;             const float mu = s1 * (1.f / 128.f), var = s2 * (1.f / 128.f) - mu * mu, rstd = 1.f / sqrtf(fmaxf(var, 0.f) + EPS);
; #pragma unroll
;             for (int vt = 0; vt < 8; ++vt) { const int cl = 16 * vt + 4 * g; const f32x4 xc = bf4_to_f32(*(const LAS u32x2*)(lds + O_XC + (16 * ti + c) * GP128 + cl * 2)), gn = *(const LAS f32x4*)(GN + cl), sk = *(const LAS f32x4*)(SK + cl);
;                 f32x4 r;
; #pragma unroll
;                 for (int i = 0; i < 4; ++i) r[i] = (a1[vt][i] - mu) * rstd * gn[i] + sk[i] * xc[i];
	v_pk_add_f32 v[130:131], v[130:131], v[140:141]
	ds_bpermute_b32 v201, v199, v131
	ds_bpermute_b32 v200, v199, v130
	ds_read_b64 v[202:203], v194 offset:52224
	ds_read_b128 v[140:143], v179
	ds_read_b128 v[144:147], v180
	v_lshlrev_b32_e32 v148, 16, v205
	v_and_b32_e32 v149, 0xffff0000, v205
	s_waitcnt lgkmcnt(2)
	v_lshlrev_b32_e32 v210, 16, v202
	v_pk_add_f32 v[130:131], v[130:131], v[200:201]
	v_and_b32_e32 v211, 0xffff0000, v202
	v_pk_mul_f32 v[130:131], v[130:131], s[4:5] op_sel_hi:[1,0]
	v_lshlrev_b32_e32 v208, 16, v203
	v_fma_f32 v2, -v131, v131, v130
	v_max_f32_e32 v2, 0, v2
	v_add_f32_e32 v2, 0x358637bd, v2
	v_mul_f32_e32 v186, 0x4f800000, v2
	v_cmp_gt_f32_e32 vcc, s68, v2
	v_pk_fma_f32 v[48:49], v[48:49], v[114:115], v[130:131] op_sel:[0,0,1] neg_lo:[0,0,1] neg_hi:[0,0,1]
	v_lshlrev_b32_e32 v150, 16, v204
	v_cndmask_b32_e32 v2, v2, v186, vcc
	v_sqrt_f32_e32 v186, v2
	v_and_b32_e32 v151, 0xffff0000, v204
	ds_read_b64 v[200:201], v195 offset:52224
	ds_read_b64 v[204:205], v196 offset:52224
	ds_read_b64 v[206:207], v197 offset:52224
	v_pk_fma_f32 v[12:13], v[80:81], v[12:13], v[130:131] op_sel:[0,0,1] neg_lo:[0,0,1] neg_hi:[0,0,1]
	v_add_u32_e32 v199, -1, v186
	v_fma_f32 v209, -v199, v186, v2
	v_cmp_ge_f32_e64 s[4:5], 0, v209
	v_add_u32_e32 v209, 1, v186
	v_pk_fma_f32 v[14:15], v[88:89], v[14:15], v[130:131] op_sel:[0,0,1] neg_lo:[0,0,1] neg_hi:[0,0,1]
	v_cndmask_b32_e64 v199, v186, v199, s[4:5]
	v_fma_f32 v186, -v209, v186, v2
	v_cmp_lt_f32_e64 s[4:5], 0, v186
	s_nop 1
	v_cndmask_b32_e64 v186, v199, v209, s[4:5]
	v_mul_f32_e32 v199, 0x37800000, v186
	v_cndmask_b32_e32 v186, v186, v199, vcc
	v_cmp_class_f32_e32 vcc, v2, v1
	v_and_b32_e32 v209, 0xffff0000, v203
	s_nop 0
	v_cndmask_b32_e32 v2, v186, v2, vcc
	v_div_scale_f32 v186, s[4:5], v2, v2, 1.0
	v_rcp_f32_e32 v199, v186
	s_mov_b64 s[4:5], 0x400
	v_lshl_add_u64 v[60:61], v[60:61], 0, s[4:5]
	s_mov_b64 s[4:5], 0x98000
	v_fma_f32 v202, -v186, v199, 1.0
	v_fmac_f32_e32 v199, v202, v199
	v_div_scale_f32 v202, vcc, 1.0, v2, 1.0
	v_mul_f32_e32 v203, v202, v199
	v_fma_f32 v212, -v186, v203, v202
	v_fmac_f32_e32 v203, v212, v199
	v_fma_f32 v186, -v186, v203, v202
	v_div_fmas_f32 v186, v186, v199, v203
	v_div_fixup_f32 v2, v186, v2, 1.0
	v_pk_mul_f32 v[48:49], v[48:49], v[2:3] op_sel_hi:[1,0]
	v_pk_mul_f32 v[12:13], v[12:13], v[2:3] op_sel_hi:[1,0]
	v_pk_mul_f32 v[16:17], v[16:17], v[48:49]
	v_pk_mul_f32 v[14:15], v[14:15], v[2:3] op_sel_hi:[1,0]
	v_pk_fma_f32 v[16:17], v[20:21], v[120:121], v[16:17]
	v_pk_fma_f32 v[20:21], v[50:51], v[108:109], v[130:131] op_sel:[0,0,1] neg_lo:[0,0,1] neg_hi:[0,0,1]
	v_cvt_pk_bf16_f32 v16, v16, v17
	v_pk_mul_f32 v[20:21], v[20:21], v[2:3] op_sel_hi:[1,0]
	s_waitcnt lgkmcnt(4)
	v_pk_mul_f32 v[12:13], v[140:141], v[12:13]
	v_pk_mul_f32 v[18:19], v[18:19], v[20:21]
	v_pk_mul_f32 v[14:15], v[142:143], v[14:15]
	v_pk_fma_f32 v[18:19], v[22:23], v[112:113], v[18:19]
	s_waitcnt lgkmcnt(3)
; #define GAS __attribute__((address_space(1)))
; #define LAS __attribute__((address_space(3)))
; __device__ __forceinline__ f32x4 bf4_to_f32(u32x2 w) { return (f32x4){bflo(w.x), bfhi(w.x), bflo(w.y), bfhi(w.y)}; }
; __device__ __forceinline__ u32x2 f32_to_bf4(f32x4 v) { u32x2 w; w.x = cvtpk(v[0], v[1]); w.y = cvtpk(v[2], v[3]); return w; }
; __device__ __forceinline__ void ml_out_unit(LAS unsigned char* lds, const MixBufs& B, int b, int h, int seg, int tid) {
;     ...
; #pragma unroll
;             for (int vt = 0; vt < 8; ++vt) { const int cl = 16 * vt + 4 * g; const f32x4 xc = bf4_to_f32(*(const LAS u32x2*)(lds + O_XC + (16 * ti + c) * GP128 + cl * 2)), gn = *(const LAS f32x4*)(GN + cl), sk = *(const LAS f32x4*)(SK + cl);
;                 f32x4 r;
; #pragma unroll
;                 for (int i = 0; i < 4; ++i) r[i] = (a1[vt][i] - mu) * rstd * gn[i] + sk[i] * xc[i];
;                 *(GAS u32x2*)(B.A_b + trow * 1024 + h * 128 + cl) = f32_to_bf4(r); }
;             m = mn;
;             __syncthreads();
	v_pk_fma_f32 v[12:13], v[144:145], v[210:211], v[12:13]
	v_cvt_pk_bf16_f32 v17, v18, v19
	global_store_dwordx2 v[110:111], v[16:17], off offset:-128
	v_pk_fma_f32 v[16:17], v[68:69], v[122:123], v[130:131] op_sel:[0,0,1] neg_lo:[0,0,1] neg_hi:[0,0,1]
	v_pk_fma_f32 v[18:19], v[70:71], v[118:119], v[130:131] op_sel:[0,0,1] neg_lo:[0,0,1] neg_hi:[0,0,1]
	v_pk_mul_f32 v[16:17], v[16:17], v[2:3] op_sel_hi:[1,0]
	v_pk_mul_f32 v[18:19], v[18:19], v[2:3] op_sel_hi:[1,0]
	v_pk_mul_f32 v[16:17], v[32:33], v[16:17]
	v_pk_mul_f32 v[18:19], v[34:35], v[18:19]
	v_pk_fma_f32 v[16:17], v[40:41], v[126:127], v[16:17]
	v_pk_fma_f32 v[18:19], v[42:43], v[116:117], v[18:19]
	v_cvt_pk_bf16_f32 v16, v16, v17
	v_cvt_pk_bf16_f32 v17, v18, v19
	global_store_dwordx2 v[110:111], v[16:17], off offset:-96
	v_pk_fma_f32 v[16:17], v[72:73], v[36:37], v[130:131] op_sel:[0,0,1] neg_lo:[0,0,1] neg_hi:[0,0,1]
	v_pk_fma_f32 v[18:19], v[74:75], v[124:125], v[130:131] op_sel:[0,0,1] neg_lo:[0,0,1] neg_hi:[0,0,1]
	v_pk_mul_f32 v[16:17], v[16:17], v[2:3] op_sel_hi:[1,0]
	v_pk_mul_f32 v[18:19], v[18:19], v[2:3] op_sel_hi:[1,0]
	v_pk_mul_f32 v[16:17], v[28:29], v[16:17]
	v_pk_mul_f32 v[18:19], v[30:31], v[18:19]
	v_pk_fma_f32 v[16:17], v[44:45], v[128:129], v[16:17]
	v_pk_fma_f32 v[18:19], v[46:47], v[38:39], v[18:19]
	v_cvt_pk_bf16_f32 v16, v16, v17
	v_cvt_pk_bf16_f32 v17, v18, v19
	global_store_dwordx2 v[110:111], v[16:17], off offset:-64
	v_pk_fma_f32 v[16:17], v[76:77], v[24:25], v[130:131] op_sel:[0,0,1] neg_lo:[0,0,1] neg_hi:[0,0,1]
	v_pk_fma_f32 v[18:19], v[78:79], v[26:27], v[130:131] op_sel:[0,0,1] neg_lo:[0,0,1] neg_hi:[0,0,1]
	v_pk_mul_f32 v[16:17], v[16:17], v[2:3] op_sel_hi:[1,0]
	v_pk_mul_f32 v[18:19], v[18:19], v[2:3] op_sel_hi:[1,0]
	v_pk_mul_f32 v[16:17], v[132:133], v[16:17]
	v_pk_mul_f32 v[18:19], v[134:135], v[18:19]
	v_pk_fma_f32 v[16:17], v[136:137], v[150:151], v[16:17]
	v_pk_fma_f32 v[18:19], v[138:139], v[148:149], v[18:19]
	v_pk_fma_f32 v[14:15], v[146:147], v[208:209], v[14:15]
	v_cvt_pk_bf16_f32 v16, v16, v17
	v_cvt_pk_bf16_f32 v17, v18, v19
	v_cvt_pk_bf16_f32 v12, v12, v13
	v_cvt_pk_bf16_f32 v13, v14, v15
	global_store_dwordx2 v[110:111], v[16:17], off offset:-32
	global_store_dwordx2 v[110:111], v[12:13], off
	ds_read_b128 v[12:15], v181
	ds_read_b128 v[16:19], v187
	s_waitcnt lgkmcnt(4)
	v_lshlrev_b32_e32 v20, 16, v200
	v_and_b32_e32 v21, 0xffff0000, v200
	v_pk_fma_f32 v[22:23], v[86:87], v[94:95], v[130:131] op_sel:[0,0,1] neg_lo:[0,0,1] neg_hi:[0,0,1]
	v_lshl_add_u64 v[64:65], v[64:65], 0, s[4:5]
	v_pk_mul_f32 v[22:23], v[22:23], v[2:3] op_sel_hi:[1,0]
	s_waitcnt lgkmcnt(0)
	v_pk_mul_f32 v[16:17], v[16:17], v[20:21]
	v_pk_fma_f32 v[20:21], v[90:91], v[92:93], v[130:131] op_sel:[0,0,1] neg_lo:[0,0,1] neg_hi:[0,0,1]
	v_pk_fma_f32 v[12:13], v[22:23], v[12:13], v[16:17]
	v_lshlrev_b32_e32 v16, 16, v201
	v_and_b32_e32 v17, 0xffff0000, v201
	v_pk_mul_f32 v[20:21], v[20:21], v[2:3] op_sel_hi:[1,0]
	v_pk_mul_f32 v[16:17], v[18:19], v[16:17]
	v_cvt_pk_bf16_f32 v12, v12, v13
	v_pk_fma_f32 v[14:15], v[20:21], v[14:15], v[16:17]
	v_lshlrev_b32_e32 v20, 16, v204
	v_cvt_pk_bf16_f32 v13, v14, v15
	global_store_dwordx2 v[110:111], v[12:13], off offset:32
	ds_read_b128 v[12:15], v188
	ds_read_b128 v[16:19], v189
	v_and_b32_e32 v21, 0xffff0000, v204
	v_pk_fma_f32 v[22:23], v[84:85], v[96:97], v[130:131] op_sel:[0,0,1] neg_lo:[0,0,1] neg_hi:[0,0,1]
	s_mov_b64 s[4:5], 0x20000
	v_pk_mul_f32 v[22:23], v[22:23], v[2:3] op_sel_hi:[1,0]
	s_waitcnt lgkmcnt(0)
	v_pk_mul_f32 v[16:17], v[16:17], v[20:21]
	v_pk_fma_f32 v[20:21], v[98:99], v[100:101], v[130:131] op_sel:[0,0,1] neg_lo:[0,0,1] neg_hi:[0,0,1]
	v_pk_fma_f32 v[12:13], v[22:23], v[12:13], v[16:17]
	v_lshlrev_b32_e32 v16, 16, v205
	v_and_b32_e32 v17, 0xffff0000, v205
	v_pk_mul_f32 v[20:21], v[20:21], v[2:3] op_sel_hi:[1,0]
	v_pk_mul_f32 v[16:17], v[18:19], v[16:17]
	v_cvt_pk_bf16_f32 v12, v12, v13
	v_pk_fma_f32 v[14:15], v[20:21], v[14:15], v[16:17]
	v_lshlrev_b32_e32 v20, 16, v206
	v_cvt_pk_bf16_f32 v13, v14, v15
	global_store_dwordx2 v[110:111], v[12:13], off offset:64
	ds_read_b128 v[12:15], v190
	ds_read_b128 v[16:19], v191
	v_and_b32_e32 v21, 0xffff0000, v206
	v_pk_fma_f32 v[22:23], v[82:83], v[102:103], v[130:131] op_sel:[0,0,1] neg_lo:[0,0,1] neg_hi:[0,0,1]
	v_lshl_add_u64 v[66:67], v[66:67], 0, s[4:5]
	v_pk_mul_f32 v[22:23], v[22:23], v[2:3] op_sel_hi:[1,0]
	s_waitcnt lgkmcnt(0)
	v_pk_mul_f32 v[16:17], v[16:17], v[20:21]
	v_pk_fma_f32 v[20:21], v[104:105], v[106:107], v[130:131] op_sel:[0,0,1] neg_lo:[0,0,1] neg_hi:[0,0,1]
	v_pk_fma_f32 v[12:13], v[22:23], v[12:13], v[16:17]
	v_lshlrev_b32_e32 v16, 16, v207
	v_and_b32_e32 v17, 0xffff0000, v207
	v_pk_mul_f32 v[20:21], v[20:21], v[2:3] op_sel_hi:[1,0]
	v_pk_mul_f32 v[16:17], v[18:19], v[16:17]
	v_cvt_pk_bf16_f32 v12, v12, v13
	v_pk_fma_f32 v[14:15], v[20:21], v[14:15], v[16:17]
	v_mov_b32_e32 v186, v198
	v_cvt_pk_bf16_f32 v13, v14, v15
	global_store_dwordx2 v[110:111], v[12:13], off offset:96
	s_barrier
	s_cbranch_scc1 .LBB0_678
